# GEMM cross-tile prefetch: next tile's first K step issued before the epilogue, entry wait vmcnt(16) leaves epilogue stores in flight
# speedup vs baseline: 1.1346x; 1.0018x over previous
.Lg2_ff2_tile:
	s_lshl_b32 s0, s64, 3
	s_add_i32 s38, s0, s68
	s_mov_b32 s69, s42
	s_mov_b32 s65, s43
	s_lshl_b32 s0, s38, 7
	s_mul_i32 s2, s69, 0x2000
	s_mul_hi_u32 s3, s69, 0x2000
	s_add_u32 s56, s26, s2
	s_addc_u32 s57, s27, s3
	s_add_u32 s56, s56, 0x0
	s_addc_u32 s57, s57, 0
	s_mul_i32 s2, s0, 0x2000
	s_mul_hi_u32 s3, s0, 0x2000
	s_add_u32 s58, s26, s2
	s_addc_u32 s59, s27, s3
	s_add_u32 s58, s58, 0x10740000
	s_addc_u32 s59, s59, 0
	s_mul_i32 s2, s69, 0x800
	s_mul_hi_u32 s3, s69, 0x800
	s_lshl_b32 s0, s0, 1
	s_add_u32 s2, s2, s0
	s_addc_u32 s3, s3, 0
	s_add_u32 s60, s26, s2
	s_addc_u32 s61, s27, s3
	s_add_u32 s60, s60, 0x11140000
	s_addc_u32 s61, s61, 0
	s_cmp_eq_u32 s65, 0
	s_cbranch_scc1 .Lg2_ff2_k16
	v_mov_b32_e32 v0, 0
	v_mov_b32_e32 v1, 0
	v_mov_b32_e32 v2, 0
	v_mov_b32_e32 v3, 0
	v_mov_b32_e32 v4, 0
	v_mov_b32_e32 v5, 0
	v_mov_b32_e32 v6, 0
	v_mov_b32_e32 v7, 0
	v_mov_b32_e32 v8, 0
	v_mov_b32_e32 v9, 0
	v_mov_b32_e32 v10, 0
	v_mov_b32_e32 v11, 0
	v_mov_b32_e32 v12, 0
	v_mov_b32_e32 v13, 0
	v_mov_b32_e32 v14, 0
	v_mov_b32_e32 v15, 0
	v_mov_b32_e32 v16, 0
	v_mov_b32_e32 v17, 0
	v_mov_b32_e32 v18, 0
	v_mov_b32_e32 v19, 0
	v_mov_b32_e32 v20, 0
	v_mov_b32_e32 v21, 0
	v_mov_b32_e32 v22, 0
	v_mov_b32_e32 v23, 0
	v_mov_b32_e32 v24, 0
	v_mov_b32_e32 v25, 0
	v_mov_b32_e32 v26, 0
	v_mov_b32_e32 v27, 0
	v_mov_b32_e32 v28, 0
	v_mov_b32_e32 v29, 0
	v_mov_b32_e32 v30, 0
	v_mov_b32_e32 v31, 0
	v_mov_b32_e32 v32, 0
	v_mov_b32_e32 v33, 0
	v_mov_b32_e32 v34, 0
	v_mov_b32_e32 v35, 0
	v_mov_b32_e32 v36, 0
	v_mov_b32_e32 v37, 0
	v_mov_b32_e32 v38, 0
	v_mov_b32_e32 v39, 0
	v_mov_b32_e32 v40, 0
	v_mov_b32_e32 v41, 0
	v_mov_b32_e32 v42, 0
	v_mov_b32_e32 v43, 0
	v_mov_b32_e32 v44, 0
	v_mov_b32_e32 v45, 0
	v_mov_b32_e32 v46, 0
	v_mov_b32_e32 v47, 0
	v_mov_b32_e32 v48, 0
	v_mov_b32_e32 v49, 0
	v_mov_b32_e32 v50, 0
	v_mov_b32_e32 v51, 0
	v_mov_b32_e32 v52, 0
	v_mov_b32_e32 v53, 0
	v_mov_b32_e32 v54, 0
	v_mov_b32_e32 v55, 0
	v_mov_b32_e32 v56, 0
	v_mov_b32_e32 v57, 0
	v_mov_b32_e32 v58, 0
	v_mov_b32_e32 v59, 0
	v_mov_b32_e32 v60, 0
	v_mov_b32_e32 v61, 0
	v_mov_b32_e32 v62, 0
	v_mov_b32_e32 v63, 0
	v_mov_b32_e32 v64, 0
	v_mov_b32_e32 v65, 0
	v_mov_b32_e32 v66, 0
	v_mov_b32_e32 v67, 0
	v_mov_b32_e32 v68, 0
	v_mov_b32_e32 v69, 0
	v_mov_b32_e32 v70, 0
	v_mov_b32_e32 v71, 0
	v_mov_b32_e32 v72, 0
	v_mov_b32_e32 v73, 0
	v_mov_b32_e32 v74, 0
	v_mov_b32_e32 v75, 0
	v_mov_b32_e32 v76, 0
	v_mov_b32_e32 v77, 0
	v_mov_b32_e32 v78, 0
	v_mov_b32_e32 v79, 0
	v_mov_b32_e32 v80, 0
	v_mov_b32_e32 v81, 0
	v_mov_b32_e32 v82, 0
	v_mov_b32_e32 v83, 0
	v_mov_b32_e32 v84, 0
	v_mov_b32_e32 v85, 0
	v_mov_b32_e32 v86, 0
	v_mov_b32_e32 v87, 0
	v_mov_b32_e32 v88, 0
	v_mov_b32_e32 v89, 0
	v_mov_b32_e32 v90, 0
	v_mov_b32_e32 v91, 0
	v_mov_b32_e32 v92, 0
	v_mov_b32_e32 v93, 0
	v_mov_b32_e32 v94, 0
	v_mov_b32_e32 v95, 0
	v_mov_b32_e32 v96, 0
	v_mov_b32_e32 v97, 0
	v_mov_b32_e32 v98, 0
	v_mov_b32_e32 v99, 0
	v_mov_b32_e32 v100, 0
	v_mov_b32_e32 v101, 0
	v_mov_b32_e32 v102, 0
	v_mov_b32_e32 v103, 0
	v_mov_b32_e32 v104, 0
	v_mov_b32_e32 v105, 0
	v_mov_b32_e32 v106, 0
	v_mov_b32_e32 v107, 0
	v_mov_b32_e32 v108, 0
	v_mov_b32_e32 v109, 0
	v_mov_b32_e32 v110, 0
	v_mov_b32_e32 v111, 0
	v_mov_b32_e32 v112, 0
	v_mov_b32_e32 v113, 0
	v_mov_b32_e32 v114, 0
	v_mov_b32_e32 v115, 0
	v_mov_b32_e32 v116, 0
	v_mov_b32_e32 v117, 0
	v_mov_b32_e32 v118, 0
	v_mov_b32_e32 v119, 0
	v_mov_b32_e32 v120, 0
	v_mov_b32_e32 v121, 0
	v_mov_b32_e32 v122, 0
	v_mov_b32_e32 v123, 0
	v_mov_b32_e32 v124, 0
	v_mov_b32_e32 v125, 0
	v_mov_b32_e32 v126, 0
	v_mov_b32_e32 v127, 0
	v_mov_b32_e32 v128, 0
	v_mov_b32_e32 v129, 0
	v_mov_b32_e32 v130, 0
	v_mov_b32_e32 v131, 0
	v_mov_b32_e32 v132, 0
	v_mov_b32_e32 v133, 0
	v_mov_b32_e32 v134, 0
	v_mov_b32_e32 v135, 0
	s_mov_b32 s63, 0
	s_add_u32 s4, s56, 0x0
	s_addc_u32 s5, s57, 0
	s_add_u32 m0, s62, 0x0
	s_nop 0
	global_load_lds_dwordx4 v162, s[4:5]
	s_add_u32 s4, s56, 0x40000
	s_addc_u32 s5, s57, 0
	s_add_u32 m0, s62, 0x1000
	s_nop 0
	global_load_lds_dwordx4 v162, s[4:5]
	s_add_u32 s4, s56, 0x80000
	s_addc_u32 s5, s57, 0
	s_add_u32 m0, s62, 0x2000
	s_nop 0
	global_load_lds_dwordx4 v162, s[4:5]
	s_add_u32 s4, s56, 0xc0000
	s_addc_u32 s5, s57, 0
	s_add_u32 m0, s62, 0x3000
	s_nop 0
	global_load_lds_dwordx4 v162, s[4:5]
	s_add_u32 s4, s56, 0x100000
	s_addc_u32 s5, s57, 0
	s_add_u32 m0, s62, 0x4000
	s_nop 0
	global_load_lds_dwordx4 v162, s[4:5]
	s_add_u32 s4, s56, 0x140000
	s_addc_u32 s5, s57, 0
	s_add_u32 m0, s62, 0x5000
	s_nop 0
	global_load_lds_dwordx4 v162, s[4:5]
	s_add_u32 s4, s56, 0x180000
	s_addc_u32 s5, s57, 0
	s_add_u32 m0, s62, 0x6000
	s_nop 0
	global_load_lds_dwordx4 v162, s[4:5]
	s_add_u32 s4, s56, 0x1c0000
	s_addc_u32 s5, s57, 0
	s_add_u32 m0, s62, 0x7000
	s_nop 0
	global_load_lds_dwordx4 v162, s[4:5]
	s_cmp_gt_u32 s70, 1
	s_cbranch_scc1 .Lg2_ff2_nodma_0
	s_add_u32 s4, s56, 0x200000
	s_addc_u32 s5, s57, 0
	s_add_u32 m0, s62, 0x8000
	s_nop 0
	global_load_lds_dwordx4 v162, s[4:5]
.Lg2_ff2_nodma_0:
	global_load_dwordx4 v[184:187], v160, s[58:59] offset:0
	global_load_dwordx4 v[188:191], v160, s[58:59] offset:1024
	global_load_dwordx4 v[192:195], v161, s[58:59] offset:0
	global_load_dwordx4 v[196:199], v161, s[58:59] offset:1024
.Lg2_ff2_loop17:
	s_waitcnt vmcnt(0)
	s_barrier
	s_add_u32 s56, s56, 0x80
	s_addc_u32 s57, s57, 0
	s_add_u32 s58, s58, 0x800
	s_addc_u32 s59, s59, 0
	s_add_u32 s4, s56, 0x0
	s_addc_u32 s5, s57, 0
	s_add_u32 m0, s62, 0x8800
	s_nop 0
	global_load_lds_dwordx4 v162, s[4:5]
	s_add_u32 s4, s56, 0x40000
	s_addc_u32 s5, s57, 0
	s_add_u32 m0, s62, 0x9800
	s_nop 0
	global_load_lds_dwordx4 v162, s[4:5]
	s_add_u32 s4, s56, 0x80000
	s_addc_u32 s5, s57, 0
	s_add_u32 m0, s62, 0xa800
	s_nop 0
	global_load_lds_dwordx4 v162, s[4:5]
	s_add_u32 s4, s56, 0xc0000
	s_addc_u32 s5, s57, 0
	s_add_u32 m0, s62, 0xb800
	s_nop 0
	global_load_lds_dwordx4 v162, s[4:5]
	s_add_u32 s4, s56, 0x100000
	s_addc_u32 s5, s57, 0
	s_add_u32 m0, s62, 0xc800
	s_nop 0
	global_load_lds_dwordx4 v162, s[4:5]
	s_add_u32 s4, s56, 0x140000
	s_addc_u32 s5, s57, 0
	s_add_u32 m0, s62, 0xd800
	s_nop 0
	global_load_lds_dwordx4 v162, s[4:5]
	s_add_u32 s4, s56, 0x180000
	s_addc_u32 s5, s57, 0
	s_add_u32 m0, s62, 0xe800
	s_nop 0
	global_load_lds_dwordx4 v162, s[4:5]
	s_add_u32 s4, s56, 0x1c0000
	s_addc_u32 s5, s57, 0
	s_add_u32 m0, s62, 0xf800
	s_nop 0
	global_load_lds_dwordx4 v162, s[4:5]
	s_cmp_gt_u32 s70, 1
	s_cbranch_scc1 .Lg2_ff2_nodma_1
	s_add_u32 s4, s56, 0x200000
	s_addc_u32 s5, s57, 0
	s_add_u32 m0, s62, 0x10800
	s_nop 0
	global_load_lds_dwordx4 v162, s[4:5]

.Lg2_ff2_k16:
	v_mov_b32_e32 v0, 0
	v_mov_b32_e32 v1, 0
	v_mov_b32_e32 v2, 0
	v_mov_b32_e32 v3, 0
	v_mov_b32_e32 v4, 0
	v_mov_b32_e32 v5, 0
	v_mov_b32_e32 v6, 0
	v_mov_b32_e32 v7, 0
	v_mov_b32_e32 v8, 0
	v_mov_b32_e32 v9, 0
	v_mov_b32_e32 v10, 0
	v_mov_b32_e32 v11, 0
	v_mov_b32_e32 v12, 0
	v_mov_b32_e32 v13, 0
	v_mov_b32_e32 v14, 0
	v_mov_b32_e32 v15, 0
	v_mov_b32_e32 v16, 0
	v_mov_b32_e32 v17, 0
	v_mov_b32_e32 v18, 0
	v_mov_b32_e32 v19, 0
	v_mov_b32_e32 v20, 0
	v_mov_b32_e32 v21, 0
	v_mov_b32_e32 v22, 0
	v_mov_b32_e32 v23, 0
	v_mov_b32_e32 v24, 0
	v_mov_b32_e32 v25, 0
	v_mov_b32_e32 v26, 0
	v_mov_b32_e32 v27, 0
	v_mov_b32_e32 v28, 0
	v_mov_b32_e32 v29, 0
	v_mov_b32_e32 v30, 0
	v_mov_b32_e32 v31, 0
	v_mov_b32_e32 v32, 0
	v_mov_b32_e32 v33, 0
	v_mov_b32_e32 v34, 0
	v_mov_b32_e32 v35, 0
	v_mov_b32_e32 v36, 0
	v_mov_b32_e32 v37, 0
	v_mov_b32_e32 v38, 0
	v_mov_b32_e32 v39, 0
	v_mov_b32_e32 v40, 0
	v_mov_b32_e32 v41, 0
	v_mov_b32_e32 v42, 0
	v_mov_b32_e32 v43, 0
	v_mov_b32_e32 v44, 0
	v_mov_b32_e32 v45, 0
	v_mov_b32_e32 v46, 0
	v_mov_b32_e32 v47, 0
	v_mov_b32_e32 v48, 0
	v_mov_b32_e32 v49, 0
	v_mov_b32_e32 v50, 0
	v_mov_b32_e32 v51, 0
	v_mov_b32_e32 v52, 0
	v_mov_b32_e32 v53, 0
	v_mov_b32_e32 v54, 0
	v_mov_b32_e32 v55, 0
	v_mov_b32_e32 v56, 0
	v_mov_b32_e32 v57, 0
	v_mov_b32_e32 v58, 0
	v_mov_b32_e32 v59, 0
	v_mov_b32_e32 v60, 0
	v_mov_b32_e32 v61, 0
	v_mov_b32_e32 v62, 0
	v_mov_b32_e32 v63, 0
	v_mov_b32_e32 v64, 0
	v_mov_b32_e32 v65, 0
	v_mov_b32_e32 v66, 0
	v_mov_b32_e32 v67, 0
	v_mov_b32_e32 v68, 0
	v_mov_b32_e32 v69, 0
	v_mov_b32_e32 v70, 0
	v_mov_b32_e32 v71, 0
	v_mov_b32_e32 v72, 0
	v_mov_b32_e32 v73, 0
	v_mov_b32_e32 v74, 0
	v_mov_b32_e32 v75, 0
	v_mov_b32_e32 v76, 0
	v_mov_b32_e32 v77, 0
	v_mov_b32_e32 v78, 0
	v_mov_b32_e32 v79, 0
	v_mov_b32_e32 v80, 0
	v_mov_b32_e32 v81, 0
	v_mov_b32_e32 v82, 0
	v_mov_b32_e32 v83, 0
	v_mov_b32_e32 v84, 0
	v_mov_b32_e32 v85, 0
	v_mov_b32_e32 v86, 0
	v_mov_b32_e32 v87, 0
	v_mov_b32_e32 v88, 0
	v_mov_b32_e32 v89, 0
	v_mov_b32_e32 v90, 0
	v_mov_b32_e32 v91, 0
	v_mov_b32_e32 v92, 0
	v_mov_b32_e32 v93, 0
	v_mov_b32_e32 v94, 0
	v_mov_b32_e32 v95, 0
	v_mov_b32_e32 v96, 0
	v_mov_b32_e32 v97, 0
	v_mov_b32_e32 v98, 0
	v_mov_b32_e32 v99, 0
	v_mov_b32_e32 v100, 0
	v_mov_b32_e32 v101, 0
	v_mov_b32_e32 v102, 0
	v_mov_b32_e32 v103, 0
	v_mov_b32_e32 v104, 0
	v_mov_b32_e32 v105, 0
	v_mov_b32_e32 v106, 0
	v_mov_b32_e32 v107, 0
	v_mov_b32_e32 v108, 0
	v_mov_b32_e32 v109, 0
	v_mov_b32_e32 v110, 0
	v_mov_b32_e32 v111, 0
	v_mov_b32_e32 v112, 0
	v_mov_b32_e32 v113, 0
	v_mov_b32_e32 v114, 0
	v_mov_b32_e32 v115, 0
	v_mov_b32_e32 v116, 0
	v_mov_b32_e32 v117, 0
	v_mov_b32_e32 v118, 0
	v_mov_b32_e32 v119, 0
	v_mov_b32_e32 v120, 0
	v_mov_b32_e32 v121, 0
	v_mov_b32_e32 v122, 0
	v_mov_b32_e32 v123, 0
	v_mov_b32_e32 v124, 0
	v_mov_b32_e32 v125, 0
	v_mov_b32_e32 v126, 0
	v_mov_b32_e32 v127, 0
	s_mov_b32 s63, 0
	s_add_u32 s4, s56, 0x0
	s_addc_u32 s5, s57, 0
	s_add_u32 m0, s62, 0x0
	s_nop 0
	global_load_lds_dwordx4 v162, s[4:5]
	s_add_u32 s4, s56, 0x40000
	s_addc_u32 s5, s57, 0
	s_add_u32 m0, s62, 0x1000
	s_nop 0
	global_load_lds_dwordx4 v162, s[4:5]
	s_add_u32 s4, s56, 0x80000
	s_addc_u32 s5, s57, 0
	s_add_u32 m0, s62, 0x2000
	s_nop 0
	global_load_lds_dwordx4 v162, s[4:5]
	s_add_u32 s4, s56, 0xc0000
	s_addc_u32 s5, s57, 0
	s_add_u32 m0, s62, 0x3000
	s_nop 0
	global_load_lds_dwordx4 v162, s[4:5]
	s_add_u32 s4, s56, 0x100000
	s_addc_u32 s5, s57, 0
	s_add_u32 m0, s62, 0x4000
	s_nop 0
	global_load_lds_dwordx4 v162, s[4:5]
	s_add_u32 s4, s56, 0x140000
	s_addc_u32 s5, s57, 0
	s_add_u32 m0, s62, 0x5000
	s_nop 0
	global_load_lds_dwordx4 v162, s[4:5]
	s_add_u32 s4, s56, 0x180000
	s_addc_u32 s5, s57, 0
	s_add_u32 m0, s62, 0x6000
	s_nop 0
	global_load_lds_dwordx4 v162, s[4:5]
	s_add_u32 s4, s56, 0x1c0000
	s_addc_u32 s5, s57, 0
	s_add_u32 m0, s62, 0x7000
	s_nop 0
	global_load_lds_dwordx4 v162, s[4:5]
	global_load_dwordx4 v[184:187], v160, s[58:59] offset:0
	global_load_dwordx4 v[188:191], v160, s[58:59] offset:1024
	global_load_dwordx4 v[192:195], v161, s[58:59] offset:0
	global_load_dwordx4 v[196:199], v161, s[58:59] offset:1024

.Lg2_ff1_tile:
	s_lshl_b32 s0, s64, 3
	s_add_i32 s38, s0, s68
	s_mov_b32 s69, s42
	s_mov_b32 s65, s43
	s_lshl_b32 s0, s38, 7
	s_mul_i32 s2, s69, 0x800
	s_mul_hi_u32 s3, s69, 0x800
	s_add_u32 s56, s26, s2
	s_addc_u32 s57, s27, s3
	s_add_u32 s56, s56, 0x13240000
	s_addc_u32 s57, s57, 0
	s_mul_i32 s2, s0, 0x800
	s_mul_hi_u32 s3, s0, 0x800
	s_add_u32 s58, s26, s2
	s_addc_u32 s59, s27, s3
	s_add_u32 s58, s58, 0xff40000
	s_addc_u32 s59, s59, 0
	s_mul_i32 s2, s69, 0x2000
	s_mul_hi_u32 s3, s69, 0x2000
	s_lshl_b32 s0, s0, 1
	s_add_u32 s2, s2, s0
	s_addc_u32 s3, s3, 0
	s_add_u32 s60, s26, s2
	s_addc_u32 s61, s27, s3
	s_add_u32 s60, s60, 0x0
	s_addc_u32 s61, s61, 0
	s_cmp_eq_u32 s65, 0
	s_cbranch_scc1 .Lg2_ff1_k16
	v_mov_b32_e32 v0, 0
	v_mov_b32_e32 v1, 0
	v_mov_b32_e32 v2, 0
	v_mov_b32_e32 v3, 0
	v_mov_b32_e32 v4, 0
	v_mov_b32_e32 v5, 0
	v_mov_b32_e32 v6, 0
	v_mov_b32_e32 v7, 0
	v_mov_b32_e32 v8, 0
	v_mov_b32_e32 v9, 0
	v_mov_b32_e32 v10, 0
	v_mov_b32_e32 v11, 0
	v_mov_b32_e32 v12, 0
	v_mov_b32_e32 v13, 0
	v_mov_b32_e32 v14, 0
	v_mov_b32_e32 v15, 0
	v_mov_b32_e32 v16, 0
	v_mov_b32_e32 v17, 0
	v_mov_b32_e32 v18, 0
	v_mov_b32_e32 v19, 0
	v_mov_b32_e32 v20, 0
	v_mov_b32_e32 v21, 0
	v_mov_b32_e32 v22, 0
	v_mov_b32_e32 v23, 0
	v_mov_b32_e32 v24, 0
	v_mov_b32_e32 v25, 0
	v_mov_b32_e32 v26, 0
	v_mov_b32_e32 v27, 0
	v_mov_b32_e32 v28, 0
	v_mov_b32_e32 v29, 0
	v_mov_b32_e32 v30, 0
	v_mov_b32_e32 v31, 0
	v_mov_b32_e32 v32, 0
	v_mov_b32_e32 v33, 0
	v_mov_b32_e32 v34, 0
	v_mov_b32_e32 v35, 0
	v_mov_b32_e32 v36, 0
	v_mov_b32_e32 v37, 0
	v_mov_b32_e32 v38, 0
	v_mov_b32_e32 v39, 0
	v_mov_b32_e32 v40, 0
	v_mov_b32_e32 v41, 0
	v_mov_b32_e32 v42, 0
	v_mov_b32_e32 v43, 0
	v_mov_b32_e32 v44, 0
	v_mov_b32_e32 v45, 0
	v_mov_b32_e32 v46, 0
	v_mov_b32_e32 v47, 0
	v_mov_b32_e32 v48, 0
	v_mov_b32_e32 v49, 0
	v_mov_b32_e32 v50, 0
	v_mov_b32_e32 v51, 0
	v_mov_b32_e32 v52, 0
	v_mov_b32_e32 v53, 0
	v_mov_b32_e32 v54, 0
	v_mov_b32_e32 v55, 0
	v_mov_b32_e32 v56, 0
	v_mov_b32_e32 v57, 0
	v_mov_b32_e32 v58, 0
	v_mov_b32_e32 v59, 0
	v_mov_b32_e32 v60, 0
	v_mov_b32_e32 v61, 0
	v_mov_b32_e32 v62, 0
	v_mov_b32_e32 v63, 0
	v_mov_b32_e32 v64, 0
	v_mov_b32_e32 v65, 0
	v_mov_b32_e32 v66, 0
	v_mov_b32_e32 v67, 0
	v_mov_b32_e32 v68, 0
	v_mov_b32_e32 v69, 0
	v_mov_b32_e32 v70, 0
	v_mov_b32_e32 v71, 0
	v_mov_b32_e32 v72, 0
	v_mov_b32_e32 v73, 0
	v_mov_b32_e32 v74, 0
	v_mov_b32_e32 v75, 0
	v_mov_b32_e32 v76, 0
	v_mov_b32_e32 v77, 0
	v_mov_b32_e32 v78, 0
	v_mov_b32_e32 v79, 0
	v_mov_b32_e32 v80, 0
	v_mov_b32_e32 v81, 0
	v_mov_b32_e32 v82, 0
	v_mov_b32_e32 v83, 0
	v_mov_b32_e32 v84, 0
	v_mov_b32_e32 v85, 0
	v_mov_b32_e32 v86, 0
	v_mov_b32_e32 v87, 0
	v_mov_b32_e32 v88, 0
	v_mov_b32_e32 v89, 0
	v_mov_b32_e32 v90, 0
	v_mov_b32_e32 v91, 0
	v_mov_b32_e32 v92, 0
	v_mov_b32_e32 v93, 0
	v_mov_b32_e32 v94, 0
	v_mov_b32_e32 v95, 0
	v_mov_b32_e32 v96, 0
	v_mov_b32_e32 v97, 0
	v_mov_b32_e32 v98, 0
	v_mov_b32_e32 v99, 0
	v_mov_b32_e32 v100, 0
	v_mov_b32_e32 v101, 0
	v_mov_b32_e32 v102, 0
	v_mov_b32_e32 v103, 0
	v_mov_b32_e32 v104, 0
	v_mov_b32_e32 v105, 0
	v_mov_b32_e32 v106, 0
	v_mov_b32_e32 v107, 0
	v_mov_b32_e32 v108, 0
	v_mov_b32_e32 v109, 0
	v_mov_b32_e32 v110, 0
	v_mov_b32_e32 v111, 0
	v_mov_b32_e32 v112, 0
	v_mov_b32_e32 v113, 0
	v_mov_b32_e32 v114, 0
	v_mov_b32_e32 v115, 0
	v_mov_b32_e32 v116, 0
	v_mov_b32_e32 v117, 0
	v_mov_b32_e32 v118, 0
	v_mov_b32_e32 v119, 0
	v_mov_b32_e32 v120, 0
	v_mov_b32_e32 v121, 0
	v_mov_b32_e32 v122, 0
	v_mov_b32_e32 v123, 0
	v_mov_b32_e32 v124, 0
	v_mov_b32_e32 v125, 0
	v_mov_b32_e32 v126, 0
	v_mov_b32_e32 v127, 0
	v_mov_b32_e32 v128, 0
	v_mov_b32_e32 v129, 0
	v_mov_b32_e32 v130, 0
	v_mov_b32_e32 v131, 0
	v_mov_b32_e32 v132, 0
	v_mov_b32_e32 v133, 0
	v_mov_b32_e32 v134, 0
	v_mov_b32_e32 v135, 0
	s_mov_b32 s63, 0
	s_cmp_eq_u32 s45, 0
	s_cbranch_scc0 .Lg2_ff1_pf17
	s_add_u32 s4, s56, 0x0
	s_addc_u32 s5, s57, 0
	s_add_u32 m0, s62, 0x0
	s_nop 0
	global_load_lds_dwordx4 v162, s[4:5]
	s_add_u32 s4, s56, 0x10000
	s_addc_u32 s5, s57, 0
	s_add_u32 m0, s62, 0x1000
	s_nop 0
	global_load_lds_dwordx4 v162, s[4:5]
	s_add_u32 s4, s56, 0x20000
	s_addc_u32 s5, s57, 0
	s_add_u32 m0, s62, 0x2000
	s_nop 0
	global_load_lds_dwordx4 v162, s[4:5]
	s_add_u32 s4, s56, 0x30000
	s_addc_u32 s5, s57, 0
	s_add_u32 m0, s62, 0x3000
	s_nop 0
	global_load_lds_dwordx4 v162, s[4:5]
	s_add_u32 s4, s56, 0x40000
	s_addc_u32 s5, s57, 0
	s_add_u32 m0, s62, 0x4000
	s_nop 0
	global_load_lds_dwordx4 v162, s[4:5]
	s_add_u32 s4, s56, 0x50000
	s_addc_u32 s5, s57, 0
	s_add_u32 m0, s62, 0x5000
	s_nop 0
	global_load_lds_dwordx4 v162, s[4:5]
	s_add_u32 s4, s56, 0x60000
	s_addc_u32 s5, s57, 0
	s_add_u32 m0, s62, 0x6000
	s_nop 0
	global_load_lds_dwordx4 v162, s[4:5]
	s_add_u32 s4, s56, 0x70000
	s_addc_u32 s5, s57, 0
	s_add_u32 m0, s62, 0x7000
	s_nop 0
	global_load_lds_dwordx4 v162, s[4:5]
	s_cmp_gt_u32 s70, 1
	s_cbranch_scc1 .Lg2_ff1_nodma_0
	s_add_u32 s4, s56, 0x80000
	s_addc_u32 s5, s57, 0
	s_add_u32 m0, s62, 0x8000
	s_nop 0
	global_load_lds_dwordx4 v162, s[4:5]

.Lg2_ff1_pf17:
	s_mov_b32 s45, 0
	s_waitcnt vmcnt(16)
	s_barrier
	s_branch .Lg2_ff1_loopin17

.Lg2_ff1_loopin17:
	s_add_u32 s56, s56, 0x80
	s_addc_u32 s57, s57, 0
	s_add_u32 s58, s58, 0x800
	s_addc_u32 s59, s59, 0
	s_add_u32 s4, s56, 0x0
	s_addc_u32 s5, s57, 0
	s_add_u32 m0, s62, 0x8800
	s_nop 0
	global_load_lds_dwordx4 v162, s[4:5]
	s_add_u32 s4, s56, 0x10000
	s_addc_u32 s5, s57, 0
	s_add_u32 m0, s62, 0x9800
	s_nop 0
	global_load_lds_dwordx4 v162, s[4:5]
	s_add_u32 s4, s56, 0x20000
	s_addc_u32 s5, s57, 0
	s_add_u32 m0, s62, 0xa800
	s_nop 0
	global_load_lds_dwordx4 v162, s[4:5]
	s_add_u32 s4, s56, 0x30000
	s_addc_u32 s5, s57, 0
	s_add_u32 m0, s62, 0xb800
	s_nop 0
	global_load_lds_dwordx4 v162, s[4:5]
	s_add_u32 s4, s56, 0x40000
	s_addc_u32 s5, s57, 0
	s_add_u32 m0, s62, 0xc800
	s_nop 0
	global_load_lds_dwordx4 v162, s[4:5]
	s_add_u32 s4, s56, 0x50000
	s_addc_u32 s5, s57, 0
	s_add_u32 m0, s62, 0xd800
	s_nop 0
	global_load_lds_dwordx4 v162, s[4:5]
	s_add_u32 s4, s56, 0x60000
	s_addc_u32 s5, s57, 0
	s_add_u32 m0, s62, 0xe800
	s_nop 0
	global_load_lds_dwordx4 v162, s[4:5]
	s_add_u32 s4, s56, 0x70000
	s_addc_u32 s5, s57, 0
	s_add_u32 m0, s62, 0xf800
	s_nop 0
	global_load_lds_dwordx4 v162, s[4:5]
	s_cmp_gt_u32 s70, 1
	s_cbranch_scc1 .Lg2_ff1_nodma_1
	s_add_u32 s4, s56, 0x80000
	s_addc_u32 s5, s57, 0
	s_add_u32 m0, s62, 0x10800
	s_nop 0
	global_load_lds_dwordx4 v162, s[4:5]

.Lg2_ff1_k16:
	v_mov_b32_e32 v0, 0
	v_mov_b32_e32 v1, 0
	v_mov_b32_e32 v2, 0
	v_mov_b32_e32 v3, 0
	v_mov_b32_e32 v4, 0
	v_mov_b32_e32 v5, 0
	v_mov_b32_e32 v6, 0
	v_mov_b32_e32 v7, 0
	v_mov_b32_e32 v8, 0
	v_mov_b32_e32 v9, 0
	v_mov_b32_e32 v10, 0
	v_mov_b32_e32 v11, 0
	v_mov_b32_e32 v12, 0
	v_mov_b32_e32 v13, 0
	v_mov_b32_e32 v14, 0
	v_mov_b32_e32 v15, 0
	v_mov_b32_e32 v16, 0
	v_mov_b32_e32 v17, 0
	v_mov_b32_e32 v18, 0
	v_mov_b32_e32 v19, 0
	v_mov_b32_e32 v20, 0
	v_mov_b32_e32 v21, 0
	v_mov_b32_e32 v22, 0
	v_mov_b32_e32 v23, 0
	v_mov_b32_e32 v24, 0
	v_mov_b32_e32 v25, 0
	v_mov_b32_e32 v26, 0
	v_mov_b32_e32 v27, 0
	v_mov_b32_e32 v28, 0
	v_mov_b32_e32 v29, 0
	v_mov_b32_e32 v30, 0
	v_mov_b32_e32 v31, 0
	v_mov_b32_e32 v32, 0
	v_mov_b32_e32 v33, 0
	v_mov_b32_e32 v34, 0
	v_mov_b32_e32 v35, 0
	v_mov_b32_e32 v36, 0
	v_mov_b32_e32 v37, 0
	v_mov_b32_e32 v38, 0
	v_mov_b32_e32 v39, 0
	v_mov_b32_e32 v40, 0
	v_mov_b32_e32 v41, 0
	v_mov_b32_e32 v42, 0
	v_mov_b32_e32 v43, 0
	v_mov_b32_e32 v44, 0
	v_mov_b32_e32 v45, 0
	v_mov_b32_e32 v46, 0
	v_mov_b32_e32 v47, 0
	v_mov_b32_e32 v48, 0
	v_mov_b32_e32 v49, 0
	v_mov_b32_e32 v50, 0
	v_mov_b32_e32 v51, 0
	v_mov_b32_e32 v52, 0
	v_mov_b32_e32 v53, 0
	v_mov_b32_e32 v54, 0
	v_mov_b32_e32 v55, 0
	v_mov_b32_e32 v56, 0
	v_mov_b32_e32 v57, 0
	v_mov_b32_e32 v58, 0
	v_mov_b32_e32 v59, 0
	v_mov_b32_e32 v60, 0
	v_mov_b32_e32 v61, 0
	v_mov_b32_e32 v62, 0
	v_mov_b32_e32 v63, 0
	v_mov_b32_e32 v64, 0
	v_mov_b32_e32 v65, 0
	v_mov_b32_e32 v66, 0
	v_mov_b32_e32 v67, 0
	v_mov_b32_e32 v68, 0
	v_mov_b32_e32 v69, 0
	v_mov_b32_e32 v70, 0
	v_mov_b32_e32 v71, 0
	v_mov_b32_e32 v72, 0
	v_mov_b32_e32 v73, 0
	v_mov_b32_e32 v74, 0
	v_mov_b32_e32 v75, 0
	v_mov_b32_e32 v76, 0
	v_mov_b32_e32 v77, 0
	v_mov_b32_e32 v78, 0
	v_mov_b32_e32 v79, 0
	v_mov_b32_e32 v80, 0
	v_mov_b32_e32 v81, 0
	v_mov_b32_e32 v82, 0
	v_mov_b32_e32 v83, 0
	v_mov_b32_e32 v84, 0
	v_mov_b32_e32 v85, 0
	v_mov_b32_e32 v86, 0
	v_mov_b32_e32 v87, 0
	v_mov_b32_e32 v88, 0
	v_mov_b32_e32 v89, 0
	v_mov_b32_e32 v90, 0
	v_mov_b32_e32 v91, 0
	v_mov_b32_e32 v92, 0
	v_mov_b32_e32 v93, 0
	v_mov_b32_e32 v94, 0
	v_mov_b32_e32 v95, 0
	v_mov_b32_e32 v96, 0
	v_mov_b32_e32 v97, 0
	v_mov_b32_e32 v98, 0
	v_mov_b32_e32 v99, 0
	v_mov_b32_e32 v100, 0
	v_mov_b32_e32 v101, 0
	v_mov_b32_e32 v102, 0
	v_mov_b32_e32 v103, 0
	v_mov_b32_e32 v104, 0
	v_mov_b32_e32 v105, 0
	v_mov_b32_e32 v106, 0
	v_mov_b32_e32 v107, 0
	v_mov_b32_e32 v108, 0
	v_mov_b32_e32 v109, 0
	v_mov_b32_e32 v110, 0
	v_mov_b32_e32 v111, 0
	v_mov_b32_e32 v112, 0
	v_mov_b32_e32 v113, 0
	v_mov_b32_e32 v114, 0
	v_mov_b32_e32 v115, 0
	v_mov_b32_e32 v116, 0
	v_mov_b32_e32 v117, 0
	v_mov_b32_e32 v118, 0
	v_mov_b32_e32 v119, 0
	v_mov_b32_e32 v120, 0
	v_mov_b32_e32 v121, 0
	v_mov_b32_e32 v122, 0
	v_mov_b32_e32 v123, 0
	v_mov_b32_e32 v124, 0
	v_mov_b32_e32 v125, 0
	v_mov_b32_e32 v126, 0
	v_mov_b32_e32 v127, 0
	s_mov_b32 s63, 0
	s_cmp_eq_u32 s45, 0
	s_cbranch_scc0 .Lg2_ff1_pf16
	s_add_u32 s4, s56, 0x0
	s_addc_u32 s5, s57, 0
	s_add_u32 m0, s62, 0x0
	s_nop 0
	global_load_lds_dwordx4 v162, s[4:5]
	s_add_u32 s4, s56, 0x10000
	s_addc_u32 s5, s57, 0
	s_add_u32 m0, s62, 0x1000
	s_nop 0
	global_load_lds_dwordx4 v162, s[4:5]
	s_add_u32 s4, s56, 0x20000
	s_addc_u32 s5, s57, 0
	s_add_u32 m0, s62, 0x2000
	s_nop 0
	global_load_lds_dwordx4 v162, s[4:5]
	s_add_u32 s4, s56, 0x30000
	s_addc_u32 s5, s57, 0
	s_add_u32 m0, s62, 0x3000
	s_nop 0
	global_load_lds_dwordx4 v162, s[4:5]
	s_add_u32 s4, s56, 0x40000
	s_addc_u32 s5, s57, 0
	s_add_u32 m0, s62, 0x4000
	s_nop 0
	global_load_lds_dwordx4 v162, s[4:5]
	s_add_u32 s4, s56, 0x50000
	s_addc_u32 s5, s57, 0
	s_add_u32 m0, s62, 0x5000
	s_nop 0
	global_load_lds_dwordx4 v162, s[4:5]
	s_add_u32 s4, s56, 0x60000
	s_addc_u32 s5, s57, 0
	s_add_u32 m0, s62, 0x6000
	s_nop 0
	global_load_lds_dwordx4 v162, s[4:5]
	s_add_u32 s4, s56, 0x70000
	s_addc_u32 s5, s57, 0
	s_add_u32 m0, s62, 0x7000
	s_nop 0
	global_load_lds_dwordx4 v162, s[4:5]
	global_load_dwordx4 v[184:187], v160, s[58:59] offset:0
	global_load_dwordx4 v[188:191], v160, s[58:59] offset:1024
	global_load_dwordx4 v[192:195], v161, s[58:59] offset:0
	global_load_dwordx4 v[196:199], v161, s[58:59] offset:1024
	s_branch .Lg2_ff1_loop16

.Lg2_ff1_loopin16:
	s_add_u32 s56, s56, 0x80
	s_addc_u32 s57, s57, 0
	s_add_u32 s58, s58, 0x800
	s_addc_u32 s59, s59, 0
	s_add_u32 s4, s56, 0x0
	s_addc_u32 s5, s57, 0
	s_add_u32 m0, s62, 0x8800
	s_nop 0
	global_load_lds_dwordx4 v162, s[4:5]
	s_add_u32 s4, s56, 0x10000
	s_addc_u32 s5, s57, 0
	s_add_u32 m0, s62, 0x9800
	s_nop 0
	global_load_lds_dwordx4 v162, s[4:5]
	s_add_u32 s4, s56, 0x20000
	s_addc_u32 s5, s57, 0
	s_add_u32 m0, s62, 0xa800
	s_nop 0
	global_load_lds_dwordx4 v162, s[4:5]
	s_add_u32 s4, s56, 0x30000
	s_addc_u32 s5, s57, 0
	s_add_u32 m0, s62, 0xb800
	s_nop 0
	global_load_lds_dwordx4 v162, s[4:5]
	s_add_u32 s4, s56, 0x40000
	s_addc_u32 s5, s57, 0
	s_add_u32 m0, s62, 0xc800
	s_nop 0
	global_load_lds_dwordx4 v162, s[4:5]
	s_add_u32 s4, s56, 0x50000
	s_addc_u32 s5, s57, 0
	s_add_u32 m0, s62, 0xd800
	s_nop 0
	global_load_lds_dwordx4 v162, s[4:5]
	s_add_u32 s4, s56, 0x60000
	s_addc_u32 s5, s57, 0
	s_add_u32 m0, s62, 0xe800
	s_nop 0
	global_load_lds_dwordx4 v162, s[4:5]
	s_add_u32 s4, s56, 0x70000
	s_addc_u32 s5, s57, 0
	s_add_u32 m0, s62, 0xf800
	s_nop 0
	global_load_lds_dwordx4 v162, s[4:5]
	global_load_dwordx4 v[200:203], v160, s[58:59] offset:0
	global_load_dwordx4 v[204:207], v160, s[58:59] offset:1024
	global_load_dwordx4 v[208:211], v161, s[58:59] offset:0
	global_load_dwordx4 v[240:243], v161, s[58:59] offset:1024
	ds_read_b128 v[136:139], v156 offset:0
	ds_read_b128 v[140:143], v156 offset:2048
	ds_read_b128 v[144:147], v156 offset:4096
	ds_read_b128 v[148:151], v156 offset:6144
	ds_read_b128 v[164:167], v156 offset:8192
	ds_read_b128 v[168:171], v156 offset:10240
	ds_read_b128 v[172:175], v156 offset:12288
	ds_read_b128 v[176:179], v156 offset:14336
	s_waitcnt lgkmcnt(4)
	v_mfma_f32_16x16x32_bf16 v[0:3], v[184:187], v[136:139], v[0:3]
	v_mfma_f32_16x16x32_bf16 v[4:7], v[192:195], v[136:139], v[4:7]
	v_mfma_f32_16x16x32_bf16 v[8:11], v[184:187], v[140:143], v[8:11]
	v_mfma_f32_16x16x32_bf16 v[12:15], v[192:195], v[140:143], v[12:15]
	v_mfma_f32_16x16x32_bf16 v[16:19], v[184:187], v[144:147], v[16:19]
	v_mfma_f32_16x16x32_bf16 v[20:23], v[192:195], v[144:147], v[20:23]
	v_mfma_f32_16x16x32_bf16 v[24:27], v[184:187], v[148:151], v[24:27]
	v_mfma_f32_16x16x32_bf16 v[28:31], v[192:195], v[148:151], v[28:31]
	ds_read_b128 v[136:139], v156 offset:16384
	ds_read_b128 v[140:143], v156 offset:18432
	ds_read_b128 v[144:147], v156 offset:20480
	ds_read_b128 v[148:151], v156 offset:22528
	s_waitcnt lgkmcnt(4)
	v_mfma_f32_16x16x32_bf16 v[32:35], v[184:187], v[164:167], v[32:35]
	v_mfma_f32_16x16x32_bf16 v[36:39], v[192:195], v[164:167], v[36:39]
	v_mfma_f32_16x16x32_bf16 v[40:43], v[184:187], v[168:171], v[40:43]
	v_mfma_f32_16x16x32_bf16 v[44:47], v[192:195], v[168:171], v[44:47]
	v_mfma_f32_16x16x32_bf16 v[48:51], v[184:187], v[172:175], v[48:51]
	v_mfma_f32_16x16x32_bf16 v[52:55], v[192:195], v[172:175], v[52:55]
	v_mfma_f32_16x16x32_bf16 v[56:59], v[184:187], v[176:179], v[56:59]
	v_mfma_f32_16x16x32_bf16 v[60:63], v[192:195], v[176:179], v[60:63]
	ds_read_b128 v[164:167], v156 offset:24576
	ds_read_b128 v[168:171], v156 offset:26624
	ds_read_b128 v[172:175], v156 offset:28672
	ds_read_b128 v[176:179], v156 offset:30720
	s_waitcnt lgkmcnt(4)
	v_mfma_f32_16x16x32_bf16 v[64:67], v[184:187], v[136:139], v[64:67]
	v_mfma_f32_16x16x32_bf16 v[68:71], v[192:195], v[136:139], v[68:71]
	v_mfma_f32_16x16x32_bf16 v[72:75], v[184:187], v[140:143], v[72:75]
	v_mfma_f32_16x16x32_bf16 v[76:79], v[192:195], v[140:143], v[76:79]
	v_mfma_f32_16x16x32_bf16 v[80:83], v[184:187], v[144:147], v[80:83]
	v_mfma_f32_16x16x32_bf16 v[84:87], v[192:195], v[144:147], v[84:87]
	v_mfma_f32_16x16x32_bf16 v[88:91], v[184:187], v[148:151], v[88:91]
	v_mfma_f32_16x16x32_bf16 v[92:95], v[192:195], v[148:151], v[92:95]
	ds_read_b128 v[136:139], v157 offset:0
	ds_read_b128 v[140:143], v157 offset:2048
	ds_read_b128 v[144:147], v157 offset:4096
	ds_read_b128 v[148:151], v157 offset:6144
	s_waitcnt lgkmcnt(4)
	v_mfma_f32_16x16x32_bf16 v[96:99], v[184:187], v[164:167], v[96:99]
	v_mfma_f32_16x16x32_bf16 v[100:103], v[192:195], v[164:167], v[100:103]
	v_mfma_f32_16x16x32_bf16 v[104:107], v[184:187], v[168:171], v[104:107]
	v_mfma_f32_16x16x32_bf16 v[108:111], v[192:195], v[168:171], v[108:111]
	v_mfma_f32_16x16x32_bf16 v[112:115], v[184:187], v[172:175], v[112:115]
	v_mfma_f32_16x16x32_bf16 v[116:119], v[192:195], v[172:175], v[116:119]
	v_mfma_f32_16x16x32_bf16 v[120:123], v[184:187], v[176:179], v[120:123]
	v_mfma_f32_16x16x32_bf16 v[124:127], v[192:195], v[176:179], v[124:127]
	ds_read_b128 v[164:167], v157 offset:8192
	ds_read_b128 v[168:171], v157 offset:10240
	ds_read_b128 v[172:175], v157 offset:12288
	ds_read_b128 v[176:179], v157 offset:14336
	s_waitcnt lgkmcnt(4)
	v_mfma_f32_16x16x32_bf16 v[0:3], v[188:191], v[136:139], v[0:3]
	v_mfma_f32_16x16x32_bf16 v[4:7], v[196:199], v[136:139], v[4:7]
	v_mfma_f32_16x16x32_bf16 v[8:11], v[188:191], v[140:143], v[8:11]
	v_mfma_f32_16x16x32_bf16 v[12:15], v[196:199], v[140:143], v[12:15]
	v_mfma_f32_16x16x32_bf16 v[16:19], v[188:191], v[144:147], v[16:19]
	v_mfma_f32_16x16x32_bf16 v[20:23], v[196:199], v[144:147], v[20:23]
	v_mfma_f32_16x16x32_bf16 v[24:27], v[188:191], v[148:151], v[24:27]
	v_mfma_f32_16x16x32_bf16 v[28:31], v[196:199], v[148:151], v[28:31]
	ds_read_b128 v[136:139], v157 offset:16384
	ds_read_b128 v[140:143], v157 offset:18432
	ds_read_b128 v[144:147], v157 offset:20480
	ds_read_b128 v[148:151], v157 offset:22528
	s_waitcnt lgkmcnt(4)
	v_mfma_f32_16x16x32_bf16 v[32:35], v[188:191], v[164:167], v[32:35]
	v_mfma_f32_16x16x32_bf16 v[36:39], v[196:199], v[164:167], v[36:39]
	v_mfma_f32_16x16x32_bf16 v[40:43], v[188:191], v[168:171], v[40:43]
	v_mfma_f32_16x16x32_bf16 v[44:47], v[196:199], v[168:171], v[44:47]
	v_mfma_f32_16x16x32_bf16 v[48:51], v[188:191], v[172:175], v[48:51]
	v_mfma_f32_16x16x32_bf16 v[52:55], v[196:199], v[172:175], v[52:55]
	v_mfma_f32_16x16x32_bf16 v[56:59], v[188:191], v[176:179], v[56:59]
	v_mfma_f32_16x16x32_bf16 v[60:63], v[196:199], v[176:179], v[60:63]
	ds_read_b128 v[164:167], v157 offset:24576
	ds_read_b128 v[168:171], v157 offset:26624
	ds_read_b128 v[172:175], v157 offset:28672
	ds_read_b128 v[176:179], v157 offset:30720
	s_waitcnt lgkmcnt(4)
	v_mfma_f32_16x16x32_bf16 v[64:67], v[188:191], v[136:139], v[64:67]
	v_mfma_f32_16x16x32_bf16 v[68:71], v[196:199], v[136:139], v[68:71]
	v_mfma_f32_16x16x32_bf16 v[72:75], v[188:191], v[140:143], v[72:75]
	v_mfma_f32_16x16x32_bf16 v[76:79], v[196:199], v[140:143], v[76:79]
	v_mfma_f32_16x16x32_bf16 v[80:83], v[188:191], v[144:147], v[80:83]
	v_mfma_f32_16x16x32_bf16 v[84:87], v[196:199], v[144:147], v[84:87]
	v_mfma_f32_16x16x32_bf16 v[88:91], v[188:191], v[148:151], v[88:91]
	v_mfma_f32_16x16x32_bf16 v[92:95], v[196:199], v[148:151], v[92:95]
	s_waitcnt lgkmcnt(0)
	v_mfma_f32_16x16x32_bf16 v[96:99], v[188:191], v[164:167], v[96:99]
	v_mfma_f32_16x16x32_bf16 v[100:103], v[196:199], v[164:167], v[100:103]
	v_mfma_f32_16x16x32_bf16 v[104:107], v[188:191], v[168:171], v[104:107]
	v_mfma_f32_16x16x32_bf16 v[108:111], v[196:199], v[168:171], v[108:111]
	v_mfma_f32_16x16x32_bf16 v[112:115], v[188:191], v[172:175], v[112:115]
	v_mfma_f32_16x16x32_bf16 v[116:119], v[196:199], v[172:175], v[116:119]
	v_mfma_f32_16x16x32_bf16 v[120:123], v[188:191], v[176:179], v[120:123]
	v_mfma_f32_16x16x32_bf16 v[124:127], v[196:199], v[176:179], v[124:127]
	s_waitcnt vmcnt(0)
	s_barrier
	s_cmp_ge_u32 s63, 14
	s_cbranch_scc1 .Lg2_ff1_last16
	s_add_u32 s56, s56, 0x80
	s_addc_u32 s57, s57, 0
	s_add_u32 s58, s58, 0x800
	s_addc_u32 s59, s59, 0
	s_add_u32 s4, s56, 0x0
	s_addc_u32 s5, s57, 0
	s_add_u32 m0, s62, 0x0
	s_nop 0
	global_load_lds_dwordx4 v162, s[4:5]
	s_add_u32 s4, s56, 0x10000
	s_addc_u32 s5, s57, 0
	s_add_u32 m0, s62, 0x1000
	s_nop 0
	global_load_lds_dwordx4 v162, s[4:5]
	s_add_u32 s4, s56, 0x20000
	s_addc_u32 s5, s57, 0
	s_add_u32 m0, s62, 0x2000
	s_nop 0
	global_load_lds_dwordx4 v162, s[4:5]
	s_add_u32 s4, s56, 0x30000
	s_addc_u32 s5, s57, 0
	s_add_u32 m0, s62, 0x3000
	s_nop 0
	global_load_lds_dwordx4 v162, s[4:5]
	s_add_u32 s4, s56, 0x40000
	s_addc_u32 s5, s57, 0
	s_add_u32 m0, s62, 0x4000
	s_nop 0
	global_load_lds_dwordx4 v162, s[4:5]
	s_add_u32 s4, s56, 0x50000
	s_addc_u32 s5, s57, 0
	s_add_u32 m0, s62, 0x5000
	s_nop 0
	global_load_lds_dwordx4 v162, s[4:5]
	s_add_u32 s4, s56, 0x60000
	s_addc_u32 s5, s57, 0
	s_add_u32 m0, s62, 0x6000
	s_nop 0
	global_load_lds_dwordx4 v162, s[4:5]
	s_add_u32 s4, s56, 0x70000
	s_addc_u32 s5, s57, 0
	s_add_u32 m0, s62, 0x7000
	s_nop 0
	global_load_lds_dwordx4 v162, s[4:5]
	global_load_dwordx4 v[184:187], v160, s[58:59] offset:0
	global_load_dwordx4 v[188:191], v160, s[58:59] offset:1024
	global_load_dwordx4 v[192:195], v161, s[58:59] offset:0
	global_load_dwordx4 v[196:199], v161, s[58:59] offset:1024
	s_branch .Lg2_ff1_noissue16

.Lg2_out_tile:
	s_lshl_b32 s0, s64, 3
	s_add_i32 s38, s0, s68
	s_mov_b32 s69, s42
	s_mov_b32 s65, s43
	s_lshl_b32 s0, s38, 7
	s_mul_i32 s2, s69, 0x800
	s_mul_hi_u32 s3, s69, 0x800
	s_add_u32 s56, s26, s2
	s_addc_u32 s57, s27, s3
	s_add_u32 s56, s56, 0x13240000
	s_addc_u32 s57, s57, 0
	s_mul_i32 s2, s0, 0x800
	s_mul_hi_u32 s3, s0, 0x800
	s_add_u32 s58, s26, s2
	s_addc_u32 s59, s27, s3
	s_add_u32 s58, s58, 0xfd40000
	s_addc_u32 s59, s59, 0
	s_mul_i32 s2, s69, 0x800
	s_mul_hi_u32 s3, s69, 0x800
	s_lshl_b32 s0, s0, 1
	s_add_u32 s2, s2, s0
	s_addc_u32 s3, s3, 0
	s_add_u32 s60, s26, s2
	s_addc_u32 s61, s27, s3
	s_add_u32 s60, s60, 0x11140000
	s_addc_u32 s61, s61, 0
	s_cmp_eq_u32 s65, 0
	s_cbranch_scc1 .Lg2_out_k16
	v_mov_b32_e32 v0, 0
	v_mov_b32_e32 v1, 0
	v_mov_b32_e32 v2, 0
	v_mov_b32_e32 v3, 0
	v_mov_b32_e32 v4, 0
	v_mov_b32_e32 v5, 0
	v_mov_b32_e32 v6, 0
	v_mov_b32_e32 v7, 0
	v_mov_b32_e32 v8, 0
	v_mov_b32_e32 v9, 0
	v_mov_b32_e32 v10, 0
	v_mov_b32_e32 v11, 0
	v_mov_b32_e32 v12, 0
	v_mov_b32_e32 v13, 0
	v_mov_b32_e32 v14, 0
	v_mov_b32_e32 v15, 0
	v_mov_b32_e32 v16, 0
	v_mov_b32_e32 v17, 0
	v_mov_b32_e32 v18, 0
	v_mov_b32_e32 v19, 0
	v_mov_b32_e32 v20, 0
	v_mov_b32_e32 v21, 0
	v_mov_b32_e32 v22, 0
	v_mov_b32_e32 v23, 0
	v_mov_b32_e32 v24, 0
	v_mov_b32_e32 v25, 0
	v_mov_b32_e32 v26, 0
	v_mov_b32_e32 v27, 0
	v_mov_b32_e32 v28, 0
	v_mov_b32_e32 v29, 0
	v_mov_b32_e32 v30, 0
	v_mov_b32_e32 v31, 0
	v_mov_b32_e32 v32, 0
	v_mov_b32_e32 v33, 0
	v_mov_b32_e32 v34, 0
	v_mov_b32_e32 v35, 0
	v_mov_b32_e32 v36, 0
	v_mov_b32_e32 v37, 0
	v_mov_b32_e32 v38, 0
	v_mov_b32_e32 v39, 0
	v_mov_b32_e32 v40, 0
	v_mov_b32_e32 v41, 0
	v_mov_b32_e32 v42, 0
	v_mov_b32_e32 v43, 0
	v_mov_b32_e32 v44, 0
	v_mov_b32_e32 v45, 0
	v_mov_b32_e32 v46, 0
	v_mov_b32_e32 v47, 0
	v_mov_b32_e32 v48, 0
	v_mov_b32_e32 v49, 0
	v_mov_b32_e32 v50, 0
	v_mov_b32_e32 v51, 0
	v_mov_b32_e32 v52, 0
	v_mov_b32_e32 v53, 0
	v_mov_b32_e32 v54, 0
	v_mov_b32_e32 v55, 0
	v_mov_b32_e32 v56, 0
	v_mov_b32_e32 v57, 0
	v_mov_b32_e32 v58, 0
	v_mov_b32_e32 v59, 0
	v_mov_b32_e32 v60, 0
	v_mov_b32_e32 v61, 0
	v_mov_b32_e32 v62, 0
	v_mov_b32_e32 v63, 0
	v_mov_b32_e32 v64, 0
	v_mov_b32_e32 v65, 0
	v_mov_b32_e32 v66, 0
	v_mov_b32_e32 v67, 0
	v_mov_b32_e32 v68, 0
	v_mov_b32_e32 v69, 0
	v_mov_b32_e32 v70, 0
	v_mov_b32_e32 v71, 0
	v_mov_b32_e32 v72, 0
	v_mov_b32_e32 v73, 0
	v_mov_b32_e32 v74, 0
	v_mov_b32_e32 v75, 0
	v_mov_b32_e32 v76, 0
	v_mov_b32_e32 v77, 0
	v_mov_b32_e32 v78, 0
	v_mov_b32_e32 v79, 0
	v_mov_b32_e32 v80, 0
	v_mov_b32_e32 v81, 0
	v_mov_b32_e32 v82, 0
	v_mov_b32_e32 v83, 0
	v_mov_b32_e32 v84, 0
	v_mov_b32_e32 v85, 0
	v_mov_b32_e32 v86, 0
	v_mov_b32_e32 v87, 0
	v_mov_b32_e32 v88, 0
	v_mov_b32_e32 v89, 0
	v_mov_b32_e32 v90, 0
	v_mov_b32_e32 v91, 0
	v_mov_b32_e32 v92, 0
	v_mov_b32_e32 v93, 0
	v_mov_b32_e32 v94, 0
	v_mov_b32_e32 v95, 0
	v_mov_b32_e32 v96, 0
	v_mov_b32_e32 v97, 0
	v_mov_b32_e32 v98, 0
	v_mov_b32_e32 v99, 0
	v_mov_b32_e32 v100, 0
	v_mov_b32_e32 v101, 0
	v_mov_b32_e32 v102, 0
	v_mov_b32_e32 v103, 0
	v_mov_b32_e32 v104, 0
	v_mov_b32_e32 v105, 0
	v_mov_b32_e32 v106, 0
	v_mov_b32_e32 v107, 0
	v_mov_b32_e32 v108, 0
	v_mov_b32_e32 v109, 0
	v_mov_b32_e32 v110, 0
	v_mov_b32_e32 v111, 0
	v_mov_b32_e32 v112, 0
	v_mov_b32_e32 v113, 0
	v_mov_b32_e32 v114, 0
	v_mov_b32_e32 v115, 0
	v_mov_b32_e32 v116, 0
	v_mov_b32_e32 v117, 0
	v_mov_b32_e32 v118, 0
	v_mov_b32_e32 v119, 0
	v_mov_b32_e32 v120, 0
	v_mov_b32_e32 v121, 0
	v_mov_b32_e32 v122, 0
	v_mov_b32_e32 v123, 0
	v_mov_b32_e32 v124, 0
	v_mov_b32_e32 v125, 0
	v_mov_b32_e32 v126, 0
	v_mov_b32_e32 v127, 0
	v_mov_b32_e32 v128, 0
	v_mov_b32_e32 v129, 0
	v_mov_b32_e32 v130, 0
	v_mov_b32_e32 v131, 0
	v_mov_b32_e32 v132, 0
	v_mov_b32_e32 v133, 0
	v_mov_b32_e32 v134, 0
	v_mov_b32_e32 v135, 0
	s_mov_b32 s63, 0
	s_add_u32 s4, s56, 0x0
	s_addc_u32 s5, s57, 0
	s_add_u32 m0, s62, 0x0
	s_nop 0
	global_load_lds_dwordx4 v162, s[4:5]
	s_add_u32 s4, s56, 0x10000
	s_addc_u32 s5, s57, 0
	s_add_u32 m0, s62, 0x1000
	s_nop 0
	global_load_lds_dwordx4 v162, s[4:5]
	s_add_u32 s4, s56, 0x20000
	s_addc_u32 s5, s57, 0
	s_add_u32 m0, s62, 0x2000
	s_nop 0
	global_load_lds_dwordx4 v162, s[4:5]
	s_add_u32 s4, s56, 0x30000
	s_addc_u32 s5, s57, 0
	s_add_u32 m0, s62, 0x3000
	s_nop 0
	global_load_lds_dwordx4 v162, s[4:5]
	s_add_u32 s4, s56, 0x40000
	s_addc_u32 s5, s57, 0
	s_add_u32 m0, s62, 0x4000
	s_nop 0
	global_load_lds_dwordx4 v162, s[4:5]
	s_add_u32 s4, s56, 0x50000
	s_addc_u32 s5, s57, 0
	s_add_u32 m0, s62, 0x5000
	s_nop 0
	global_load_lds_dwordx4 v162, s[4:5]
	s_add_u32 s4, s56, 0x60000
	s_addc_u32 s5, s57, 0
	s_add_u32 m0, s62, 0x6000
	s_nop 0
	global_load_lds_dwordx4 v162, s[4:5]
	s_add_u32 s4, s56, 0x70000
	s_addc_u32 s5, s57, 0
	s_add_u32 m0, s62, 0x7000
	s_nop 0
	global_load_lds_dwordx4 v162, s[4:5]
	s_cmp_gt_u32 s70, 1
	s_cbranch_scc1 .Lg2_out_nodma_0
	s_add_u32 s4, s56, 0x80000
	s_addc_u32 s5, s57, 0
	s_add_u32 m0, s62, 0x8000
	s_nop 0
	global_load_lds_dwordx4 v162, s[4:5]
.Lg2_out_nodma_0:
	global_load_dwordx4 v[184:187], v160, s[58:59] offset:0
	global_load_dwordx4 v[188:191], v160, s[58:59] offset:1024
	global_load_dwordx4 v[192:195], v161, s[58:59] offset:0
	global_load_dwordx4 v[196:199], v161, s[58:59] offset:1024
.Lg2_out_loop17:
	s_waitcnt vmcnt(0)
	s_barrier
	s_add_u32 s56, s56, 0x80
	s_addc_u32 s57, s57, 0
	s_add_u32 s58, s58, 0x800
	s_addc_u32 s59, s59, 0
	s_add_u32 s4, s56, 0x0
	s_addc_u32 s5, s57, 0
	s_add_u32 m0, s62, 0x8800
	s_nop 0
	global_load_lds_dwordx4 v162, s[4:5]
	s_add_u32 s4, s56, 0x10000
	s_addc_u32 s5, s57, 0
	s_add_u32 m0, s62, 0x9800
	s_nop 0
	global_load_lds_dwordx4 v162, s[4:5]
	s_add_u32 s4, s56, 0x20000
	s_addc_u32 s5, s57, 0
	s_add_u32 m0, s62, 0xa800
	s_nop 0
	global_load_lds_dwordx4 v162, s[4:5]
	s_add_u32 s4, s56, 0x30000
	s_addc_u32 s5, s57, 0
	s_add_u32 m0, s62, 0xb800
	s_nop 0
	global_load_lds_dwordx4 v162, s[4:5]
	s_add_u32 s4, s56, 0x40000
	s_addc_u32 s5, s57, 0
	s_add_u32 m0, s62, 0xc800
	s_nop 0
	global_load_lds_dwordx4 v162, s[4:5]
	s_add_u32 s4, s56, 0x50000
	s_addc_u32 s5, s57, 0
	s_add_u32 m0, s62, 0xd800
	s_nop 0
	global_load_lds_dwordx4 v162, s[4:5]
	s_add_u32 s4, s56, 0x60000
	s_addc_u32 s5, s57, 0
	s_add_u32 m0, s62, 0xe800
	s_nop 0
	global_load_lds_dwordx4 v162, s[4:5]
	s_add_u32 s4, s56, 0x70000
	s_addc_u32 s5, s57, 0
	s_add_u32 m0, s62, 0xf800
	s_nop 0
	global_load_lds_dwordx4 v162, s[4:5]
	s_cmp_gt_u32 s70, 1
	s_cbranch_scc1 .Lg2_out_nodma_1
	s_add_u32 s4, s56, 0x80000
	s_addc_u32 s5, s57, 0
	s_add_u32 m0, s62, 0x10800
	s_nop 0
	global_load_lds_dwordx4 v162, s[4:5]

.Lg2_out_k16:
	v_mov_b32_e32 v0, 0
	v_mov_b32_e32 v1, 0
	v_mov_b32_e32 v2, 0
	v_mov_b32_e32 v3, 0
	v_mov_b32_e32 v4, 0
	v_mov_b32_e32 v5, 0
	v_mov_b32_e32 v6, 0
	v_mov_b32_e32 v7, 0
	v_mov_b32_e32 v8, 0
	v_mov_b32_e32 v9, 0
	v_mov_b32_e32 v10, 0
	v_mov_b32_e32 v11, 0
	v_mov_b32_e32 v12, 0
	v_mov_b32_e32 v13, 0
	v_mov_b32_e32 v14, 0
	v_mov_b32_e32 v15, 0
	v_mov_b32_e32 v16, 0
	v_mov_b32_e32 v17, 0
	v_mov_b32_e32 v18, 0
	v_mov_b32_e32 v19, 0
	v_mov_b32_e32 v20, 0
	v_mov_b32_e32 v21, 0
	v_mov_b32_e32 v22, 0
	v_mov_b32_e32 v23, 0
	v_mov_b32_e32 v24, 0
	v_mov_b32_e32 v25, 0
	v_mov_b32_e32 v26, 0
	v_mov_b32_e32 v27, 0
	v_mov_b32_e32 v28, 0
	v_mov_b32_e32 v29, 0
	v_mov_b32_e32 v30, 0
	v_mov_b32_e32 v31, 0
	v_mov_b32_e32 v32, 0
	v_mov_b32_e32 v33, 0
	v_mov_b32_e32 v34, 0
	v_mov_b32_e32 v35, 0
	v_mov_b32_e32 v36, 0
	v_mov_b32_e32 v37, 0
	v_mov_b32_e32 v38, 0
	v_mov_b32_e32 v39, 0
	v_mov_b32_e32 v40, 0
	v_mov_b32_e32 v41, 0
	v_mov_b32_e32 v42, 0
	v_mov_b32_e32 v43, 0
	v_mov_b32_e32 v44, 0
	v_mov_b32_e32 v45, 0
	v_mov_b32_e32 v46, 0
	v_mov_b32_e32 v47, 0
	v_mov_b32_e32 v48, 0
	v_mov_b32_e32 v49, 0
	v_mov_b32_e32 v50, 0
	v_mov_b32_e32 v51, 0
	v_mov_b32_e32 v52, 0
	v_mov_b32_e32 v53, 0
	v_mov_b32_e32 v54, 0
	v_mov_b32_e32 v55, 0
	v_mov_b32_e32 v56, 0
	v_mov_b32_e32 v57, 0
	v_mov_b32_e32 v58, 0
	v_mov_b32_e32 v59, 0
	v_mov_b32_e32 v60, 0
	v_mov_b32_e32 v61, 0
	v_mov_b32_e32 v62, 0
	v_mov_b32_e32 v63, 0
	v_mov_b32_e32 v64, 0
	v_mov_b32_e32 v65, 0
	v_mov_b32_e32 v66, 0
	v_mov_b32_e32 v67, 0
	v_mov_b32_e32 v68, 0
	v_mov_b32_e32 v69, 0
	v_mov_b32_e32 v70, 0
	v_mov_b32_e32 v71, 0
	v_mov_b32_e32 v72, 0
	v_mov_b32_e32 v73, 0
	v_mov_b32_e32 v74, 0
	v_mov_b32_e32 v75, 0
	v_mov_b32_e32 v76, 0
	v_mov_b32_e32 v77, 0
	v_mov_b32_e32 v78, 0
	v_mov_b32_e32 v79, 0
	v_mov_b32_e32 v80, 0
	v_mov_b32_e32 v81, 0
	v_mov_b32_e32 v82, 0
	v_mov_b32_e32 v83, 0
	v_mov_b32_e32 v84, 0
	v_mov_b32_e32 v85, 0
	v_mov_b32_e32 v86, 0
	v_mov_b32_e32 v87, 0
	v_mov_b32_e32 v88, 0
	v_mov_b32_e32 v89, 0
	v_mov_b32_e32 v90, 0
	v_mov_b32_e32 v91, 0
	v_mov_b32_e32 v92, 0
	v_mov_b32_e32 v93, 0
	v_mov_b32_e32 v94, 0
	v_mov_b32_e32 v95, 0
	v_mov_b32_e32 v96, 0
	v_mov_b32_e32 v97, 0
	v_mov_b32_e32 v98, 0
	v_mov_b32_e32 v99, 0
	v_mov_b32_e32 v100, 0
	v_mov_b32_e32 v101, 0
	v_mov_b32_e32 v102, 0
	v_mov_b32_e32 v103, 0
	v_mov_b32_e32 v104, 0
	v_mov_b32_e32 v105, 0
	v_mov_b32_e32 v106, 0
	v_mov_b32_e32 v107, 0
	v_mov_b32_e32 v108, 0
	v_mov_b32_e32 v109, 0
	v_mov_b32_e32 v110, 0
	v_mov_b32_e32 v111, 0
	v_mov_b32_e32 v112, 0
	v_mov_b32_e32 v113, 0
	v_mov_b32_e32 v114, 0
	v_mov_b32_e32 v115, 0
	v_mov_b32_e32 v116, 0
	v_mov_b32_e32 v117, 0
	v_mov_b32_e32 v118, 0
	v_mov_b32_e32 v119, 0
	v_mov_b32_e32 v120, 0
	v_mov_b32_e32 v121, 0
	v_mov_b32_e32 v122, 0
	v_mov_b32_e32 v123, 0
	v_mov_b32_e32 v124, 0
	v_mov_b32_e32 v125, 0
	v_mov_b32_e32 v126, 0
	v_mov_b32_e32 v127, 0
	s_mov_b32 s63, 0
	s_add_u32 s4, s56, 0x0
	s_addc_u32 s5, s57, 0
	s_add_u32 m0, s62, 0x0
	s_nop 0
	global_load_lds_dwordx4 v162, s[4:5]
	s_add_u32 s4, s56, 0x10000
	s_addc_u32 s5, s57, 0
	s_add_u32 m0, s62, 0x1000
	s_nop 0
	global_load_lds_dwordx4 v162, s[4:5]
	s_add_u32 s4, s56, 0x20000
	s_addc_u32 s5, s57, 0
	s_add_u32 m0, s62, 0x2000
	s_nop 0
	global_load_lds_dwordx4 v162, s[4:5]
	s_add_u32 s4, s56, 0x30000
	s_addc_u32 s5, s57, 0
	s_add_u32 m0, s62, 0x3000
	s_nop 0
	global_load_lds_dwordx4 v162, s[4:5]
	s_add_u32 s4, s56, 0x40000
	s_addc_u32 s5, s57, 0
	s_add_u32 m0, s62, 0x4000
	s_nop 0
	global_load_lds_dwordx4 v162, s[4:5]
	s_add_u32 s4, s56, 0x50000
	s_addc_u32 s5, s57, 0
	s_add_u32 m0, s62, 0x5000
	s_nop 0
	global_load_lds_dwordx4 v162, s[4:5]
	s_add_u32 s4, s56, 0x60000
	s_addc_u32 s5, s57, 0
	s_add_u32 m0, s62, 0x6000
	s_nop 0
	global_load_lds_dwordx4 v162, s[4:5]
	s_add_u32 s4, s56, 0x70000
	s_addc_u32 s5, s57, 0
	s_add_u32 m0, s62, 0x7000
	s_nop 0
	global_load_lds_dwordx4 v162, s[4:5]
	global_load_dwordx4 v[184:187], v160, s[58:59] offset:0
	global_load_dwordx4 v[188:191], v160, s[58:59] offset:1024
	global_load_dwordx4 v[192:195], v161, s[58:59] offset:0
	global_load_dwordx4 v[196:199], v161, s[58:59] offset:1024

.Lg2_win_tile:
	s_lshl_b32 s0, s64, 3
	s_add_i32 s38, s0, s68
	s_mov_b32 s69, s42
	s_mov_b32 s65, s43
	s_lshl_b32 s0, s38, 7
	s_mul_i32 s2, s69, 0x800
	s_mul_hi_u32 s3, s69, 0x800
	s_add_u32 s56, s26, s2
	s_addc_u32 s57, s27, s3
	s_add_u32 s56, s56, 0x11140000
	s_addc_u32 s57, s57, 0
	s_mul_i32 s2, s0, 0x800
	s_mul_hi_u32 s3, s0, 0x800
	s_add_u32 s58, s26, s2
	s_addc_u32 s59, s27, s3
	s_add_u32 s58, s58, 0xeb20000
	s_addc_u32 s59, s59, 0
	s_mul_i32 s2, s69, 0x3900
	s_mul_hi_u32 s3, s69, 0x3900
	s_lshl_b32 s0, s0, 1
	s_add_u32 s2, s2, s0
	s_addc_u32 s3, s3, 0
	s_add_u32 s60, s26, s2
	s_addc_u32 s61, s27, s3
	s_add_u32 s60, s60, 0x0
	s_addc_u32 s61, s61, 0
	s_cmp_eq_u32 s65, 0
	s_cbranch_scc1 .Lg2_win_k16
	v_mov_b32_e32 v0, 0
	v_mov_b32_e32 v1, 0
	v_mov_b32_e32 v2, 0
	v_mov_b32_e32 v3, 0
	v_mov_b32_e32 v4, 0
	v_mov_b32_e32 v5, 0
	v_mov_b32_e32 v6, 0
	v_mov_b32_e32 v7, 0
	v_mov_b32_e32 v8, 0
	v_mov_b32_e32 v9, 0
	v_mov_b32_e32 v10, 0
	v_mov_b32_e32 v11, 0
	v_mov_b32_e32 v12, 0
	v_mov_b32_e32 v13, 0
	v_mov_b32_e32 v14, 0
	v_mov_b32_e32 v15, 0
	v_mov_b32_e32 v16, 0
	v_mov_b32_e32 v17, 0
	v_mov_b32_e32 v18, 0
	v_mov_b32_e32 v19, 0
	v_mov_b32_e32 v20, 0
	v_mov_b32_e32 v21, 0
	v_mov_b32_e32 v22, 0
	v_mov_b32_e32 v23, 0
	v_mov_b32_e32 v24, 0
	v_mov_b32_e32 v25, 0
	v_mov_b32_e32 v26, 0
	v_mov_b32_e32 v27, 0
	v_mov_b32_e32 v28, 0
	v_mov_b32_e32 v29, 0
	v_mov_b32_e32 v30, 0
	v_mov_b32_e32 v31, 0
	v_mov_b32_e32 v32, 0
	v_mov_b32_e32 v33, 0
	v_mov_b32_e32 v34, 0
	v_mov_b32_e32 v35, 0
	v_mov_b32_e32 v36, 0
	v_mov_b32_e32 v37, 0
	v_mov_b32_e32 v38, 0
	v_mov_b32_e32 v39, 0
	v_mov_b32_e32 v40, 0
	v_mov_b32_e32 v41, 0
	v_mov_b32_e32 v42, 0
	v_mov_b32_e32 v43, 0
	v_mov_b32_e32 v44, 0
	v_mov_b32_e32 v45, 0
	v_mov_b32_e32 v46, 0
	v_mov_b32_e32 v47, 0
	v_mov_b32_e32 v48, 0
	v_mov_b32_e32 v49, 0
	v_mov_b32_e32 v50, 0
	v_mov_b32_e32 v51, 0
	v_mov_b32_e32 v52, 0
	v_mov_b32_e32 v53, 0
	v_mov_b32_e32 v54, 0
	v_mov_b32_e32 v55, 0
	v_mov_b32_e32 v56, 0
	v_mov_b32_e32 v57, 0
	v_mov_b32_e32 v58, 0
	v_mov_b32_e32 v59, 0
	v_mov_b32_e32 v60, 0
	v_mov_b32_e32 v61, 0
	v_mov_b32_e32 v62, 0
	v_mov_b32_e32 v63, 0
	v_mov_b32_e32 v64, 0
	v_mov_b32_e32 v65, 0
	v_mov_b32_e32 v66, 0
	v_mov_b32_e32 v67, 0
	v_mov_b32_e32 v68, 0
	v_mov_b32_e32 v69, 0
	v_mov_b32_e32 v70, 0
	v_mov_b32_e32 v71, 0
	v_mov_b32_e32 v72, 0
	v_mov_b32_e32 v73, 0
	v_mov_b32_e32 v74, 0
	v_mov_b32_e32 v75, 0
	v_mov_b32_e32 v76, 0
	v_mov_b32_e32 v77, 0
	v_mov_b32_e32 v78, 0
	v_mov_b32_e32 v79, 0
	v_mov_b32_e32 v80, 0
	v_mov_b32_e32 v81, 0
	v_mov_b32_e32 v82, 0
	v_mov_b32_e32 v83, 0
	v_mov_b32_e32 v84, 0
	v_mov_b32_e32 v85, 0
	v_mov_b32_e32 v86, 0
	v_mov_b32_e32 v87, 0
	v_mov_b32_e32 v88, 0
	v_mov_b32_e32 v89, 0
	v_mov_b32_e32 v90, 0
	v_mov_b32_e32 v91, 0
	v_mov_b32_e32 v92, 0
	v_mov_b32_e32 v93, 0
	v_mov_b32_e32 v94, 0
	v_mov_b32_e32 v95, 0
	v_mov_b32_e32 v96, 0
	v_mov_b32_e32 v97, 0
	v_mov_b32_e32 v98, 0
	v_mov_b32_e32 v99, 0
	v_mov_b32_e32 v100, 0
	v_mov_b32_e32 v101, 0
	v_mov_b32_e32 v102, 0
	v_mov_b32_e32 v103, 0
	v_mov_b32_e32 v104, 0
	v_mov_b32_e32 v105, 0
	v_mov_b32_e32 v106, 0
	v_mov_b32_e32 v107, 0
	v_mov_b32_e32 v108, 0
	v_mov_b32_e32 v109, 0
	v_mov_b32_e32 v110, 0
	v_mov_b32_e32 v111, 0
	v_mov_b32_e32 v112, 0
	v_mov_b32_e32 v113, 0
	v_mov_b32_e32 v114, 0
	v_mov_b32_e32 v115, 0
	v_mov_b32_e32 v116, 0
	v_mov_b32_e32 v117, 0
	v_mov_b32_e32 v118, 0
	v_mov_b32_e32 v119, 0
	v_mov_b32_e32 v120, 0
	v_mov_b32_e32 v121, 0
	v_mov_b32_e32 v122, 0
	v_mov_b32_e32 v123, 0
	v_mov_b32_e32 v124, 0
	v_mov_b32_e32 v125, 0
	v_mov_b32_e32 v126, 0
	v_mov_b32_e32 v127, 0
	v_mov_b32_e32 v128, 0
	v_mov_b32_e32 v129, 0
	v_mov_b32_e32 v130, 0
	v_mov_b32_e32 v131, 0
	v_mov_b32_e32 v132, 0
	v_mov_b32_e32 v133, 0
	v_mov_b32_e32 v134, 0
	v_mov_b32_e32 v135, 0
	s_mov_b32 s63, 0
	s_cmp_eq_u32 s45, 0
	s_cbranch_scc0 .Lg2_win_pf17
	s_add_u32 s4, s56, 0x0
	s_addc_u32 s5, s57, 0
	s_add_u32 m0, s62, 0x0
	s_nop 0
	global_load_lds_dwordx4 v162, s[4:5]
	s_add_u32 s4, s56, 0x10000
	s_addc_u32 s5, s57, 0
	s_add_u32 m0, s62, 0x1000
	s_nop 0
	global_load_lds_dwordx4 v162, s[4:5]
	s_add_u32 s4, s56, 0x20000
	s_addc_u32 s5, s57, 0
	s_add_u32 m0, s62, 0x2000
	s_nop 0
	global_load_lds_dwordx4 v162, s[4:5]
	s_add_u32 s4, s56, 0x30000
	s_addc_u32 s5, s57, 0
	s_add_u32 m0, s62, 0x3000
	s_nop 0
	global_load_lds_dwordx4 v162, s[4:5]
	s_add_u32 s4, s56, 0x40000
	s_addc_u32 s5, s57, 0
	s_add_u32 m0, s62, 0x4000
	s_nop 0
	global_load_lds_dwordx4 v162, s[4:5]
	s_add_u32 s4, s56, 0x50000
	s_addc_u32 s5, s57, 0
	s_add_u32 m0, s62, 0x5000
	s_nop 0
	global_load_lds_dwordx4 v162, s[4:5]
	s_add_u32 s4, s56, 0x60000
	s_addc_u32 s5, s57, 0
	s_add_u32 m0, s62, 0x6000
	s_nop 0
	global_load_lds_dwordx4 v162, s[4:5]
	s_add_u32 s4, s56, 0x70000
	s_addc_u32 s5, s57, 0
	s_add_u32 m0, s62, 0x7000
	s_nop 0
	global_load_lds_dwordx4 v162, s[4:5]
	s_cmp_gt_u32 s70, 1
	s_cbranch_scc1 .Lg2_win_nodma_0
	s_add_u32 s4, s56, 0x80000
	s_addc_u32 s5, s57, 0
	s_add_u32 m0, s62, 0x8000
	s_nop 0
	global_load_lds_dwordx4 v162, s[4:5]

.Lg2_win_next:
	s_add_i32 s64, s64, 1
	s_cmp_lt_u32 s64, 7
	s_cbranch_scc1 .Lg2_win_tile
	v_lshrrev_b32_e32 v4, 6, v163
	v_and_b32_e32 v5, 63, v163
	v_and_b32_e32 v6, 15, v5
	v_lshrrev_b32_e32 v7, 4, v5
	v_lshlrev_b32_e32 v11, 1, v4
	s_mov_b32 s2, 0x8000
	v_mul_lo_u32 v12, v11, s2
	v_lshl_add_u32 v160, v5, 4, v12
	v_add_u32_e32 v161, 0x8000, v160
	v_lshrrev_b32_e32 v12, 1, v7
	v_lshl_add_u32 v12, v11, 1, v12
	v_and_b32_e32 v13, 1, v7
	v_lshlrev_b32_e32 v13, 3, v13
	v_lshl_add_u32 v14, v6, 8, v13
	v_xor_b32_e32 v15, v12, v6
	v_lshlrev_b32_e32 v15, 4, v15
	v_add_u32_e32 v212, v14, v15
	v_add_u32_e32 v12, 2, v12
	v_xor_b32_e32 v15, v12, v6
	v_lshlrev_b32_e32 v15, 4, v15
	v_add_u32_e32 v213, v14, v15
	v_add_u32_e32 v253, 0x8000, v212
	v_add_u32_e32 v254, 0x8000, v213
	s_mov_b32 s38, 56
	s_lshl_b32 s0, s68, 5
	s_add_i32 s69, s42, s0
	s_cmp_eq_u32 s68, 7
	s_cselect_b32 s0, 1, 0
	s_and_b32 s65, s0, s43
	s_lshl_b32 s0, s38, 7
	s_mul_i32 s2, s69, 0x800
	s_mul_hi_u32 s3, s69, 0x800
	s_add_u32 s56, s26, s2
	s_addc_u32 s57, s27, s3
	s_add_u32 s56, s56, 0x11140000
	s_addc_u32 s57, s57, 0
	s_mul_i32 s2, s0, 0x800
	s_mul_hi_u32 s3, s0, 0x800
	s_add_u32 s58, s26, s2
	s_addc_u32 s59, s27, s3
	s_add_u32 s58, s58, 0xeb20000
	s_addc_u32 s59, s59, 0
	s_mul_i32 s2, s69, 0x3900
	s_mul_hi_u32 s3, s69, 0x3900
	s_lshl_b32 s0, s0, 1
	s_add_u32 s2, s2, s0
	s_addc_u32 s3, s3, 0
	s_add_u32 s60, s26, s2
	s_addc_u32 s61, s27, s3
	s_add_u32 s60, s60, 0x0
	s_addc_u32 s61, s61, 0
	s_cmp_eq_u32 s65, 0
	s_cbranch_scc1 .Lg2_win_k2
	v_mov_b32_e32 v0, 0
	v_mov_b32_e32 v1, 0
	v_mov_b32_e32 v2, 0
	v_mov_b32_e32 v3, 0
	v_mov_b32_e32 v4, 0
	v_mov_b32_e32 v5, 0
	v_mov_b32_e32 v6, 0
	v_mov_b32_e32 v7, 0
	v_mov_b32_e32 v8, 0
	v_mov_b32_e32 v9, 0
	v_mov_b32_e32 v10, 0
	v_mov_b32_e32 v11, 0
	v_mov_b32_e32 v12, 0
	v_mov_b32_e32 v13, 0
	v_mov_b32_e32 v14, 0
	v_mov_b32_e32 v15, 0
	v_mov_b32_e32 v16, 0
	v_mov_b32_e32 v17, 0
	v_mov_b32_e32 v18, 0
	v_mov_b32_e32 v19, 0
	v_mov_b32_e32 v20, 0
	v_mov_b32_e32 v21, 0
	v_mov_b32_e32 v22, 0
	v_mov_b32_e32 v23, 0
	s_mov_b32 s63, 0
	s_add_u32 s4, s56, 0x0
	s_addc_u32 s5, s57, 0
	s_add_u32 m0, s62, 0x0
	s_nop 0
	global_load_lds_dwordx4 v162, s[4:5]
	s_cmp_gt_u32 s70, 1
	s_cbranch_scc1 .Lg2_win_nodma_4
	s_add_u32 s4, s56, 0x10000
	s_addc_u32 s5, s57, 0
	s_add_u32 m0, s62, 0x1000
	s_nop 0
	global_load_lds_dwordx4 v162, s[4:5]
.Lg2_win_nodma_4:
	global_load_dwordx4 v[184:187], v160, s[58:59] offset:0
	global_load_dwordx4 v[188:191], v160, s[58:59] offset:1024
	global_load_dwordx4 v[192:195], v161, s[58:59] offset:0
	global_load_dwordx4 v[196:199], v161, s[58:59] offset:1024
.Lg2_win_loop3:
	s_waitcnt vmcnt(0)
	s_barrier
	s_add_u32 s56, s56, 0x80
	s_addc_u32 s57, s57, 0
	s_add_u32 s58, s58, 0x800
	s_addc_u32 s59, s59, 0
	s_add_u32 s4, s56, 0x0
	s_addc_u32 s5, s57, 0
	s_add_u32 m0, s62, 0x8800
	s_nop 0
	global_load_lds_dwordx4 v162, s[4:5]
	s_cmp_gt_u32 s70, 1
	s_cbranch_scc1 .Lg2_win_nodma_5
	s_add_u32 s4, s56, 0x10000
	s_addc_u32 s5, s57, 0
	s_add_u32 m0, s62, 0x9800
	s_nop 0
	global_load_lds_dwordx4 v162, s[4:5]

.Lg2_win_k2:
	v_mov_b32_e32 v0, 0
	v_mov_b32_e32 v1, 0
	v_mov_b32_e32 v2, 0
	v_mov_b32_e32 v3, 0
	v_mov_b32_e32 v4, 0
	v_mov_b32_e32 v5, 0
	v_mov_b32_e32 v6, 0
	v_mov_b32_e32 v7, 0
	v_mov_b32_e32 v8, 0
	v_mov_b32_e32 v9, 0
	v_mov_b32_e32 v10, 0
	v_mov_b32_e32 v11, 0
	v_mov_b32_e32 v12, 0
	v_mov_b32_e32 v13, 0
	v_mov_b32_e32 v14, 0
	v_mov_b32_e32 v15, 0
	s_mov_b32 s63, 0
	s_add_u32 s4, s56, 0x0
	s_addc_u32 s5, s57, 0
	s_add_u32 m0, s62, 0x0
	s_nop 0
	global_load_lds_dwordx4 v162, s[4:5]
	global_load_dwordx4 v[184:187], v160, s[58:59] offset:0
	global_load_dwordx4 v[188:191], v160, s[58:59] offset:1024
	global_load_dwordx4 v[192:195], v161, s[58:59] offset:0
	global_load_dwordx4 v[196:199], v161, s[58:59] offset:1024
